# FFN-down k-loops (phases 6, 13): 32-bit lane offsets plus scalar base pairs (saddr loads) instead of nine 64-bit VALU address adds per k-tile
# speedup vs baseline: 1.0181x; 1.0181x over previous
.LBB0_759:
	s_lshr_b32 s6, s28, 3
	s_and_b32 s29, s6, 24
	s_lshl_b32 s6, s29, 3
	s_sub_i32 s6, s28, s6
	s_ashr_i32 s17, s6, 3
	s_and_b32 s6, s28, 7
	s_or_b32 s6, s6, s3
	s_or_b32 s16, s6, s29
	v_mad_i64_i32 v[34:35], s[6:7], s17, v171, v[116:117]
	s_mul_i32 s10, s16, 0xb0000
	v_lshl_add_u64 v[36:37], v[118:119], 0, s[10:11]
	v_add_co_u32_e32 v22, vcc, s21, v34
	v_lshl_add_u64 v[2:3], v[36:37], 0, v[130:131]
	v_lshl_add_u64 v[10:11], v[36:37], 0, v[132:133]
	v_addc_co_u32_e32 v23, vcc, 0, v35, vcc
	v_lshl_add_u64 v[14:15], v[36:37], 0, v[134:135]
	s_barrier
	global_load_dwordx4 v[2:5], v[2:3], off
	s_waitcnt lgkmcnt(0)
	global_load_dwordx4 v[6:9], v[34:35], off
	s_nop 0
	global_load_dwordx4 v[10:13], v[10:11], off
	s_nop 0
	global_load_dwordx4 v[14:17], v[14:15], off
	s_nop 0
	global_load_dwordx4 v[18:21], v[22:23], off offset:-4096
	s_nop 0
	global_load_dwordx4 v[22:25], v[22:23], off
	v_add_co_u32_e32 v38, vcc, s22, v34
	v_lshl_add_u64 v[26:27], v[36:37], 0, v[136:137]
	s_nop 0
	v_addc_co_u32_e32 v39, vcc, 0, v35, vcc
	v_add_co_u32_e32 v44, vcc, s23, v34
	v_lshl_add_u64 v[36:37], v[36:37], 0, s[12:13]
	s_nop 0
	v_addc_co_u32_e32 v45, vcc, 0, v35, vcc
	global_load_dwordx4 v[26:29], v[26:27], off
	v_lshl_add_u64 v[40:41], v[36:37], 0, v[130:131]
	v_lshl_add_u64 v[42:43], v[36:37], 0, v[132:133]
	v_lshl_add_u64 v[46:47], v[36:37], 0, v[134:135]
	v_lshl_add_u64 v[36:37], v[36:37], 0, v[136:137]
	v_add_co_u32_e32 v34, vcc, 0x7000, v34
	global_load_dwordx4 v[30:33], v[38:39], off offset:-4096
	global_load_dwordx4 v[90:93], v[40:41], off
	global_load_dwordx4 v[94:97], v[38:39], off
	global_load_dwordx4 v[82:85], v[42:43], off
	global_load_dwordx4 v[70:73], v[46:47], off
	global_load_dwordx4 v[86:89], v[44:45], off offset:-4096
	global_load_dwordx4 v[74:77], v[44:45], off
	v_addc_co_u32_e32 v35, vcc, 0, v35, vcc
	global_load_dwordx4 v[66:69], v[36:37], off
	global_load_dwordx4 v[78:81], v[34:35], off
	s_and_b32 s6, s2, 7
	s_add_i32 s7, s3, s29
	s_add_i32 s29, s7, s6
	s_mov_b64 s[14:15], 0
	s_mov_b32 s10, 0
	v_mad_u64_u32 v[138:139], s[6:7], s29, v171, v[122:123]
	v_mad_u64_u32 v[140:141], s[6:7], s29, v171, v[124:125]
	v_mad_u64_u32 v[142:143], s[6:7], s29, v171, v[126:127]
	v_mad_u64_u32 v[144:145], s[6:7], s29, v171, v[128:129]
	v_mad_i64_i32 v[146:147], s[6:7], s17, v171, v[120:121]
	v_mov_b32_e32 v34, v115
	v_mov_b32_e32 v35, v115
	v_mov_b32_e32 v36, v115
	v_mov_b32_e32 v37, v115
	v_mov_b32_e32 v38, v115
	v_mov_b32_e32 v39, v115
	v_mov_b32_e32 v40, v115
	v_mov_b32_e32 v41, v115
	v_mov_b32_e32 v42, v115
	v_mov_b32_e32 v43, v115
	v_mov_b32_e32 v44, v115
	v_mov_b32_e32 v45, v115
	v_mov_b32_e32 v46, v115
	v_mov_b32_e32 v47, v115
	v_mov_b32_e32 v48, v115
	v_mov_b32_e32 v49, v115
	v_mov_b32_e32 v50, v115
	v_mov_b32_e32 v51, v115
	v_mov_b32_e32 v52, v115
	v_mov_b32_e32 v53, v115
	v_mov_b32_e32 v54, v115
	v_mov_b32_e32 v55, v115
	v_mov_b32_e32 v56, v115
	v_mov_b32_e32 v57, v115
	v_mov_b32_e32 v58, v115
	v_mov_b32_e32 v59, v115
	v_mov_b32_e32 v60, v115
	s_waitcnt vmcnt(15)
	ds_write_b128 v150, v[2:5]
	s_waitcnt vmcnt(14)
	ds_write_b128 v150, v[6:9] offset:18432
	s_waitcnt vmcnt(13)
	ds_write_b128 v152, v[10:13]
	s_waitcnt vmcnt(11)
	ds_write_b128 v152, v[18:21] offset:18432
	ds_write_b128 v154, v[14:17]
	s_waitcnt vmcnt(10)
	ds_write_b128 v154, v[22:25] offset:18432
	s_waitcnt vmcnt(9)
	ds_write_b128 v156, v[26:29]
	s_waitcnt vmcnt(8)
	ds_write_b128 v156, v[30:33] offset:18432
	s_waitcnt lgkmcnt(0)
	s_barrier
	ds_read_b128 v[98:101], v172 offset:4608
	ds_read_b128 v[110:113], v172
	ds_read_b128 v[102:105], v173 offset:23040
	ds_read_b128 v[106:109], v173 offset:18432
	v_mov_b32_e32 v2, v115
	v_mov_b32_e32 v3, v115
	v_mov_b32_e32 v4, v115
	v_mov_b32_e32 v5, v115
	v_mov_b32_e32 v6, v115
	v_mov_b32_e32 v7, v115
	v_mov_b32_e32 v8, v115
	v_mov_b32_e32 v9, v115
	v_mov_b32_e32 v10, v115
	v_mov_b32_e32 v11, v115
	v_mov_b32_e32 v12, v115
	v_mov_b32_e32 v13, v115
	v_mov_b32_e32 v14, v115
	v_mov_b32_e32 v15, v115
	v_mov_b32_e32 v16, v115
	v_mov_b32_e32 v17, v115
	v_mov_b32_e32 v18, v115
	v_mov_b32_e32 v19, v115
	v_mov_b32_e32 v20, v115
	v_mov_b32_e32 v21, v115
	v_mov_b32_e32 v22, v115
	v_mov_b32_e32 v23, v115
	v_mov_b32_e32 v24, v115
	v_mov_b32_e32 v25, v115
	v_mov_b32_e32 v26, v115
	v_mov_b32_e32 v27, v115
	v_mov_b32_e32 v28, v115
	v_mov_b32_e32 v29, v115
	v_mov_b32_e32 v30, v115
	v_mov_b32_e32 v31, v115
	v_mov_b32_e32 v32, v115
	v_mov_b32_e32 v33, v115
	v_mov_b32_e32 v61, v115
	v_mov_b32_e32 v62, v115
	v_mov_b32_e32 v63, v115
	v_mov_b32_e32 v64, v115
	v_mov_b32_e32 v65, v115
	v_subrev_u32_e32 v240, s34, v138
	v_subrev_u32_e32 v241, s34, v140
	v_subrev_u32_e32 v242, s34, v142
	v_subrev_u32_e32 v243, s34, v144
	v_subrev_u32_e32 v244, s34, v146
.LBB0_760:
	s_add_u32 s62, s34, s14
	s_addc_u32 s63, s35, s15
	s_add_u32 s64, s62, s24
	s_addc_u32 s65, s63, 0
	s_add_u32 s76, s62, s25
	s_addc_u32 s77, s63, 0
	s_and_b32 s6, s10, 1
	s_xor_b32 s7, s6, 1
	s_mul_i32 s29, s7, 0x9000
	v_lshl_or_b32 v178, v148, 1, s29
	v_lshl_add_u32 v179, v149, 1, v178
	s_waitcnt lgkmcnt(0)
	v_mfma_f32_32x32x16_bf16 v[50:65], v[106:109], v[110:113], v[50:65]
	s_waitcnt vmcnt(7)
	ds_write_b128 v179, v[90:93]
	v_lshl_add_u32 v90, v151, 1, v178
	s_waitcnt vmcnt(6)
	ds_write_b128 v179, v[94:97] offset:18432
	s_mul_i32 s6, s6, 0x9000
	v_mfma_f32_32x32x16_bf16 v[34:49], v[102:105], v[110:113], v[34:49]
	s_waitcnt vmcnt(5)
	ds_write_b128 v90, v[82:85]
	v_lshl_add_u32 v82, v153, 1, v178
	v_lshl_add_u32 v83, v155, 1, v178
	s_waitcnt vmcnt(3)
	ds_write_b128 v90, v[86:89] offset:18432
	v_mfma_f32_32x32x16_bf16 v[18:33], v[106:109], v[98:101], v[18:33]
	v_add3_u32 v106, s6, v157, v159
	s_waitcnt vmcnt(1)
	ds_write_b128 v82, v[70:73]
	s_waitcnt vmcnt(2)
	ds_write_b128 v82, v[74:77] offset:18432
	v_add3_u32 v107, s6, v158, v159
	v_mfma_f32_32x32x16_bf16 v[2:17], v[102:105], v[98:101], v[2:17]
	s_waitcnt vmcnt(0)
	ds_write_b128 v83, v[66:69]
	s_waitcnt vmcnt(0)
	ds_write_b128 v83, v[78:81] offset:18432
	ds_read_b128 v[66:69], v106 offset:23072
	ds_read_b128 v[70:73], v107 offset:4640
	global_load_dwordx4 v[90:93], v240, s[62:63]
	s_waitcnt lgkmcnt(0)
	v_mfma_f32_32x32x16_bf16 v[2:17], v[66:69], v[70:73], v[2:17]
	ds_read_b128 v[74:77], v106 offset:18464
	ds_read_b128 v[98:101], v106 offset:18496
	global_load_dwordx4 v[94:97], v244, s[64:65] offset:-4096
	global_load_dwordx4 v[82:85], v241, s[62:63]
	global_load_dwordx4 v[86:89], v244, s[64:65]
	s_waitcnt lgkmcnt(1)
	v_mfma_f32_32x32x16_bf16 v[18:33], v[74:77], v[70:73], v[18:33]
	ds_read_b128 v[70:73], v107 offset:32
	ds_read_b128 v[102:105], v107 offset:64
	v_or_b32_e32 v108, s29, v159
	v_add_u32_e32 v198, v108, v158
	s_add_i32 s10, s10, 1
	s_add_u32 s14, s14, 0x4000
	s_addc_u32 s15, s15, 0
	s_waitcnt lgkmcnt(1)
	v_mfma_f32_32x32x16_bf16 v[50:65], v[74:77], v[70:73], v[50:65]
	ds_read_b128 v[174:177], v106 offset:23104
	ds_read_b128 v[178:181], v107 offset:4672
	global_load_dwordx4 v[74:77], v244, s[76:77] offset:-4096
	s_cmp_eq_u32 s14, 0xa8000
	global_load_dwordx4 v[78:81], v244, s[76:77]
	v_mfma_f32_32x32x16_bf16 v[34:49], v[66:69], v[70:73], v[34:49]
	global_load_dwordx4 v[70:73], v242, s[62:63]
	global_load_dwordx4 v[66:69], v243, s[62:63]
	ds_read_b128 v[182:185], v106 offset:18528
	ds_read_b128 v[186:189], v107 offset:96
	s_waitcnt lgkmcnt(4)
	v_mfma_f32_32x32x16_bf16 v[50:65], v[98:101], v[102:105], v[50:65]
	ds_read_b128 v[190:193], v106 offset:23136
	ds_read_b128 v[194:197], v107 offset:4704
	s_waitcnt lgkmcnt(0)
	s_barrier
	v_mfma_f32_32x32x16_bf16 v[34:49], v[174:177], v[102:105], v[34:49]
	v_add_u32_e32 v102, v108, v157
	ds_read_b128 v[106:109], v102 offset:18432
	ds_read_b128 v[110:113], v198
	v_mfma_f32_32x32x16_bf16 v[18:33], v[98:101], v[178:181], v[18:33]
	ds_read_b128 v[102:105], v102 offset:23040
	ds_read_b128 v[98:101], v198 offset:4608
	v_mfma_f32_32x32x16_bf16 v[2:17], v[174:177], v[178:181], v[2:17]
	v_mfma_f32_32x32x16_bf16 v[50:65], v[182:185], v[186:189], v[50:65]
	v_mfma_f32_32x32x16_bf16 v[34:49], v[190:193], v[186:189], v[34:49]
	v_mfma_f32_32x32x16_bf16 v[18:33], v[182:185], v[194:197], v[18:33]
	v_mfma_f32_32x32x16_bf16 v[2:17], v[190:193], v[194:197], v[2:17]
	s_cbranch_scc0 .LBB0_760
	s_waitcnt lgkmcnt(2)
	v_mfma_f32_32x32x16_bf16 v[50:65], v[106:109], v[110:113], v[50:65]
	s_waitcnt vmcnt(7)
	ds_write_b128 v150, v[90:93] offset:36864
	s_waitcnt vmcnt(6)
	ds_write_b128 v150, v[94:97] offset:55296
	s_lshl_b32 s6, s17, 1
	s_ashr_i32 s7, s6, 31
	s_lshl_b32 s10, s16, 7
	s_lshl_b64 s[6:7], s[6:7], 2
	s_add_u32 s6, s44, s6
	s_waitcnt lgkmcnt(3)
	v_mfma_f32_32x32x16_bf16 v[34:49], v[102:105], v[110:113], v[34:49]
	s_waitcnt vmcnt(5)
	ds_write_b128 v152, v[82:85] offset:36864
	s_waitcnt vmcnt(4)
	ds_write_b128 v152, v[86:89] offset:55296
	s_addc_u32 s7, s45, s7
	s_mov_b64 s[14:15], -1
	s_waitcnt lgkmcnt(4)
	v_mfma_f32_32x32x16_bf16 v[18:33], v[106:109], v[98:101], v[18:33]
	s_waitcnt vmcnt(1)
	ds_write_b128 v154, v[70:73] offset:36864
	ds_write_b128 v154, v[74:77] offset:55296
	v_mfma_f32_32x32x16_bf16 v[2:17], v[102:105], v[98:101], v[2:17]
	s_waitcnt vmcnt(0)
	ds_write_b128 v156, v[66:69] offset:36864
	ds_write_b128 v156, v[78:81] offset:55296
	ds_read_b128 v[66:69], v169 offset:23072
	ds_read_b128 v[70:73], v170 offset:4640
	s_waitcnt lgkmcnt(0)
	v_mfma_f32_32x32x16_bf16 v[2:17], v[66:69], v[70:73], v[2:17]
	ds_read_b128 v[74:77], v169 offset:18464
	ds_read_b128 v[78:81], v169 offset:18496
	s_waitcnt lgkmcnt(1)
	v_mfma_f32_32x32x16_bf16 v[18:33], v[74:77], v[70:73], v[18:33]
	ds_read_b128 v[70:73], v170 offset:32
	ds_read_b128 v[82:85], v170 offset:64
	s_waitcnt lgkmcnt(1)
	v_mfma_f32_32x32x16_bf16 v[50:65], v[74:77], v[70:73], v[50:65]
	ds_read_b128 v[74:77], v169 offset:23104
	ds_read_b128 v[86:89], v170 offset:4672
	v_mfma_f32_32x32x16_bf16 v[34:49], v[66:69], v[70:73], v[34:49]
	ds_read_b128 v[66:69], v169 offset:18528
	ds_read_b128 v[70:73], v170 offset:96
	s_waitcnt lgkmcnt(4)
	v_mfma_f32_32x32x16_bf16 v[50:65], v[78:81], v[82:85], v[50:65]
	ds_read_b128 v[90:93], v169 offset:23136
	ds_read_b128 v[94:97], v170 offset:4704
	s_waitcnt lgkmcnt(0)
	s_barrier
	v_mfma_f32_32x32x16_bf16 v[34:49], v[74:77], v[82:85], v[34:49]
	ds_read_b128 v[82:85], v173 offset:55296
	ds_read_b128 v[98:101], v172 offset:36864
	v_mfma_f32_32x32x16_bf16 v[18:33], v[78:81], v[86:89], v[18:33]
	ds_read_b128 v[78:81], v173 offset:59904
	ds_read_b128 v[102:105], v172 offset:41472
	v_mfma_f32_32x32x16_bf16 v[2:17], v[74:77], v[86:89], v[2:17]
	ds_read_b128 v[74:77], v169 offset:59936
	ds_read_b128 v[86:89], v170 offset:41504
	v_mfma_f32_32x32x16_bf16 v[50:65], v[66:69], v[70:73], v[50:65]
	ds_read_b128 v[106:109], v169 offset:55328
	ds_read_b128 v[110:113], v169 offset:55360
	v_mfma_f32_32x32x16_bf16 v[34:49], v[90:93], v[70:73], v[34:49]
	ds_read_b128 v[70:73], v170 offset:36896
	ds_read_b128 v[138:141], v170 offset:36928
	v_mfma_f32_32x32x16_bf16 v[18:33], v[66:69], v[94:97], v[18:33]
	ds_read_b128 v[66:69], v169 offset:59968
	ds_read_b128 v[142:145], v170 offset:41536
	v_mfma_f32_32x32x16_bf16 v[2:17], v[90:93], v[94:97], v[2:17]
	ds_read_b128 v[90:93], v169 offset:55392
	ds_read_b128 v[94:97], v170 offset:36960
	s_waitcnt lgkmcnt(12)
	v_mfma_f32_32x32x16_bf16 v[50:65], v[82:85], v[98:101], v[50:65]
	ds_read_b128 v[174:177], v169 offset:60000
	ds_read_b128 v[178:181], v170 offset:41568
	s_waitcnt lgkmcnt(0)
	s_barrier
	s_barrier
	v_mfma_f32_32x32x16_bf16 v[34:49], v[78:81], v[98:101], v[34:49]
	v_mfma_f32_32x32x16_bf16 v[18:33], v[82:85], v[102:105], v[18:33]
	v_mfma_f32_32x32x16_bf16 v[2:17], v[78:81], v[102:105], v[2:17]
	v_mfma_f32_32x32x16_bf16 v[50:65], v[106:109], v[70:73], v[50:65]
	v_mfma_f32_32x32x16_bf16 v[34:49], v[74:77], v[70:73], v[34:49]
	v_mfma_f32_32x32x16_bf16 v[18:33], v[106:109], v[86:89], v[18:33]
	v_mfma_f32_32x32x16_bf16 v[2:17], v[74:77], v[86:89], v[2:17]
	v_mfma_f32_32x32x16_bf16 v[50:65], v[110:113], v[138:141], v[50:65]
	v_mfma_f32_32x32x16_bf16 v[34:49], v[66:69], v[138:141], v[34:49]
	v_mfma_f32_32x32x16_bf16 v[18:33], v[110:113], v[142:145], v[18:33]
	v_mfma_f32_32x32x16_bf16 v[2:17], v[66:69], v[142:145], v[2:17]
	v_mfma_f32_32x32x16_bf16 v[50:65], v[90:93], v[94:97], v[50:65]
	s_nop 11
	ds_write_b128 v160, v[50:53]
	ds_write_b128 v160, v[54:57] offset:32
	v_mfma_f32_32x32x16_bf16 v[34:49], v[174:177], v[94:97], v[34:49]
	ds_write_b128 v160, v[58:61] offset:64
	ds_write_b128 v160, v[62:65] offset:96
	v_mfma_f32_32x32x16_bf16 v[18:33], v[90:93], v[178:181], v[18:33]
	s_nop 8
	ds_write_b128 v160, v[34:37] offset:128
	ds_write_b128 v160, v[38:41] offset:160
	v_mfma_f32_32x32x16_bf16 v[2:17], v[174:177], v[178:181], v[2:17]
	ds_write_b128 v160, v[42:45] offset:192
	ds_write_b128 v160, v[46:49] offset:224
	ds_write_b128 v160, v[18:21] offset:16896
	ds_write_b128 v160, v[22:25] offset:16928
	ds_write_b128 v160, v[26:29] offset:16960
	ds_write_b128 v160, v[30:33] offset:16992
	v_or_b32_e32 v20, s10, v1
	s_nop 4
	ds_write_b128 v160, v[2:5] offset:17024
	v_lshl_or_b32 v2, s17, 7, v161
	v_ashrrev_i32_e32 v21, 6, v2
	v_lshl_add_u32 v2, s16, 4, v21
	v_ashrrev_i32_e32 v3, 31, v2
	v_lshlrev_b64 v[2:3], 14, v[2:3]
	v_lshl_add_u64 v[2:3], s[92:93], 0, v[2:3]
	v_lshl_add_u64 v[4:5], v[2:3], 0, v[114:115]
	s_mov_b32 s16, 0
	ds_write_b128 v160, v[6:9] offset:17056
	ds_write_b128 v160, v[10:13] offset:17088
	ds_write_b128 v160, v[14:17] offset:17120
	s_waitcnt lgkmcnt(0)
	s_barrier
	s_branch .LBB0_763

.LBB0_2476:
	s_lshr_b32 s2, s22, 3
	s_and_b32 s25, s2, 24
	s_lshl_b32 s2, s25, 3
	s_sub_i32 s2, s22, s2
	s_ashr_i32 s24, s2, 3
	s_and_b32 s2, s22, 7
	s_or_b32 s2, s2, s13
	s_or_b32 s23, s2, s25
	s_mul_i32 s6, s23, 0xb0000
	v_mad_i64_i32 v[34:35], s[2:3], s24, v168, v[116:117]
	v_lshl_add_u64 v[36:37], v[118:119], 0, s[6:7]
	v_lshl_add_u64 v[10:11], v[36:37], 0, v[130:131]
	v_lshl_add_u64 v[26:27], v[36:37], 0, v[132:133]
	v_add_co_u32_e32 v28, vcc, s17, v34
	s_waitcnt vmcnt(63) expcnt(7) lgkmcnt(15)
	s_barrier
	global_load_dwordx4 v[2:5], v[10:11], off
	global_load_dwordx4 v[6:9], v[34:35], off
	v_addc_co_u32_e32 v29, vcc, 0, v35, vcc
	v_lshl_add_u64 v[30:31], v[36:37], 0, v[134:135]
	global_load_dwordx4 v[10:13], v[26:27], off
	global_load_dwordx4 v[14:17], v[30:31], off
	global_load_dwordx4 v[18:21], v[28:29], off offset:-4096
	global_load_dwordx4 v[22:25], v[28:29], off
	v_add_co_u32_e32 v38, vcc, s18, v34
	v_lshl_add_u64 v[26:27], v[36:37], 0, v[136:137]
	s_nop 0
	v_addc_co_u32_e32 v39, vcc, 0, v35, vcc
	v_add_co_u32_e32 v44, vcc, s19, v34
	v_lshl_add_u64 v[36:37], v[36:37], 0, s[8:9]
	s_nop 0
	v_addc_co_u32_e32 v45, vcc, 0, v35, vcc
	global_load_dwordx4 v[26:29], v[26:27], off
	v_lshl_add_u64 v[40:41], v[36:37], 0, v[130:131]
	v_lshl_add_u64 v[42:43], v[36:37], 0, v[132:133]
	v_lshl_add_u64 v[46:47], v[36:37], 0, v[134:135]
	v_lshl_add_u64 v[36:37], v[36:37], 0, v[136:137]
	v_add_co_u32_e32 v34, vcc, 0x7000, v34
	global_load_dwordx4 v[30:33], v[38:39], off offset:-4096
	global_load_dwordx4 v[90:93], v[40:41], off
	global_load_dwordx4 v[94:97], v[38:39], off
	global_load_dwordx4 v[82:85], v[42:43], off
	global_load_dwordx4 v[66:69], v[46:47], off
	global_load_dwordx4 v[86:89], v[44:45], off offset:-4096
	global_load_dwordx4 v[74:77], v[44:45], off
	v_addc_co_u32_e32 v35, vcc, 0, v35, vcc
	global_load_dwordx4 v[70:73], v[36:37], off
	global_load_dwordx4 v[78:81], v[34:35], off
	s_and_b32 s2, s12, 7
	s_add_i32 s3, s13, s25
	s_add_i32 s25, s3, s2
	s_mov_b64 s[10:11], 0
	s_mov_b32 s6, 0
	v_mad_u64_u32 v[140:141], s[2:3], s25, v168, v[122:123]
	v_mad_u64_u32 v[142:143], s[2:3], s25, v168, v[124:125]
	v_mad_u64_u32 v[144:145], s[2:3], s25, v168, v[126:127]
	v_mad_u64_u32 v[146:147], s[2:3], s25, v168, v[128:129]
	v_mad_i64_i32 v[148:149], s[2:3], s24, v168, v[120:121]
	v_mov_b32_e32 v34, v115
	v_mov_b32_e32 v35, v115
	v_mov_b32_e32 v36, v115
	v_mov_b32_e32 v37, v115
	v_mov_b32_e32 v38, v115
	v_mov_b32_e32 v39, v115
	v_mov_b32_e32 v40, v115
	v_mov_b32_e32 v41, v115
	v_mov_b32_e32 v42, v115
	v_mov_b32_e32 v43, v115
	v_mov_b32_e32 v44, v115
	v_mov_b32_e32 v45, v115
	v_mov_b32_e32 v46, v115
	v_mov_b32_e32 v47, v115
	v_mov_b32_e32 v48, v115
	v_mov_b32_e32 v49, v115
	v_mov_b32_e32 v50, v115
	v_mov_b32_e32 v51, v115
	v_mov_b32_e32 v52, v115
	v_mov_b32_e32 v53, v115
	v_mov_b32_e32 v54, v115
	v_mov_b32_e32 v55, v115
	v_mov_b32_e32 v56, v115
	v_mov_b32_e32 v57, v115
	v_mov_b32_e32 v58, v115
	v_mov_b32_e32 v59, v115
	v_mov_b32_e32 v60, v115
	s_waitcnt vmcnt(15)
	ds_write_b128 v152, v[2:5]
	s_waitcnt vmcnt(14)
	ds_write_b128 v152, v[6:9] offset:18432
	s_waitcnt vmcnt(13)
	ds_write_b128 v154, v[10:13]
	s_waitcnt vmcnt(11)
	ds_write_b128 v154, v[18:21] offset:18432
	ds_write_b128 v156, v[14:17]
	s_waitcnt vmcnt(10)
	ds_write_b128 v156, v[22:25] offset:18432
	s_waitcnt vmcnt(9)
	ds_write_b128 v158, v[26:29]
	s_waitcnt vmcnt(8)
	ds_write_b128 v158, v[30:33] offset:18432
	s_waitcnt lgkmcnt(0)
	s_barrier
	ds_read_b128 v[106:109], v169 offset:18432
	ds_read_b128 v[98:101], v169 offset:23040
	ds_read_b128 v[110:113], v170
	ds_read_b128 v[102:105], v170 offset:4608
	v_mov_b32_e32 v2, v115
	v_mov_b32_e32 v3, v115
	v_mov_b32_e32 v4, v115
	v_mov_b32_e32 v5, v115
	v_mov_b32_e32 v6, v115
	v_mov_b32_e32 v7, v115
	v_mov_b32_e32 v8, v115
	v_mov_b32_e32 v9, v115
	v_mov_b32_e32 v10, v115
	v_mov_b32_e32 v11, v115
	v_mov_b32_e32 v12, v115
	v_mov_b32_e32 v13, v115
	v_mov_b32_e32 v14, v115
	v_mov_b32_e32 v15, v115
	v_mov_b32_e32 v16, v115
	v_mov_b32_e32 v17, v115
	v_mov_b32_e32 v18, v115
	v_mov_b32_e32 v19, v115
	v_mov_b32_e32 v20, v115
	v_mov_b32_e32 v21, v115
	v_mov_b32_e32 v22, v115
	v_mov_b32_e32 v23, v115
	v_mov_b32_e32 v24, v115
	v_mov_b32_e32 v25, v115
	v_mov_b32_e32 v26, v115
	v_mov_b32_e32 v27, v115
	v_mov_b32_e32 v28, v115
	v_mov_b32_e32 v29, v115
	v_mov_b32_e32 v30, v115
	v_mov_b32_e32 v31, v115
	v_mov_b32_e32 v32, v115
	v_mov_b32_e32 v33, v115
	v_mov_b32_e32 v61, v115
	v_mov_b32_e32 v62, v115
	v_mov_b32_e32 v63, v115
	v_mov_b32_e32 v64, v115
	v_mov_b32_e32 v65, v115
	v_subrev_u32_e32 v240, s34, v140
	v_subrev_u32_e32 v241, s34, v142
	v_subrev_u32_e32 v242, s34, v144
	v_subrev_u32_e32 v243, s34, v146
	v_subrev_u32_e32 v244, s34, v148
.LBB0_2477:
	s_add_u32 s62, s34, s10
	s_addc_u32 s63, s35, s11
	s_add_u32 s64, s62, s20
	s_addc_u32 s65, s63, 0
	s_add_u32 s76, s62, s21
	s_addc_u32 s77, s63, 0
	s_and_b32 s2, s6, 1
	s_xor_b32 s3, s2, 1
	s_mul_i32 s25, s3, 0x9000
	v_lshl_or_b32 v114, v150, 1, s25
	v_lshl_add_u32 v139, v151, 1, v114
	s_waitcnt lgkmcnt(1)
	v_mfma_f32_32x32x16_bf16 v[50:65], v[106:109], v[110:113], v[50:65]
	s_waitcnt vmcnt(7)
	ds_write_b128 v139, v[90:93]
	v_lshl_add_u32 v90, v153, 1, v114
	s_waitcnt vmcnt(6)
	ds_write_b128 v139, v[94:97] offset:18432
	s_mul_i32 s2, s2, 0x9000
	v_mfma_f32_32x32x16_bf16 v[34:49], v[98:101], v[110:113], v[34:49]
	s_waitcnt vmcnt(5)
	ds_write_b128 v90, v[82:85]
	v_lshl_add_u32 v82, v155, 1, v114
	v_lshl_add_u32 v83, v157, 1, v114
	s_waitcnt vmcnt(3)
	ds_write_b128 v90, v[86:89] offset:18432
	s_waitcnt lgkmcnt(4)
	v_mfma_f32_32x32x16_bf16 v[18:33], v[106:109], v[102:105], v[18:33]
	v_add3_u32 v106, s2, v160, v159
	s_waitcnt vmcnt(1)
	ds_write_b128 v82, v[66:69]
	s_waitcnt vmcnt(2)
	ds_write_b128 v82, v[74:77] offset:18432
	v_add3_u32 v107, s2, v161, v159
	v_mfma_f32_32x32x16_bf16 v[2:17], v[98:101], v[102:105], v[2:17]
	s_waitcnt vmcnt(0)
	ds_write_b128 v83, v[70:73]
	s_waitcnt vmcnt(0)
	ds_write_b128 v83, v[78:81] offset:18432
	ds_read_b128 v[66:69], v106 offset:23072
	ds_read_b128 v[70:73], v107 offset:4640
	global_load_dwordx4 v[90:93], v240, s[62:63]
	s_waitcnt lgkmcnt(0)
	v_mfma_f32_32x32x16_bf16 v[2:17], v[66:69], v[70:73], v[2:17]
	ds_read_b128 v[74:77], v106 offset:18464
	ds_read_b128 v[98:101], v106 offset:18496
	global_load_dwordx4 v[94:97], v244, s[64:65] offset:-4096
	global_load_dwordx4 v[82:85], v241, s[62:63]
	global_load_dwordx4 v[86:89], v244, s[64:65]
	s_waitcnt lgkmcnt(1)
	v_mfma_f32_32x32x16_bf16 v[18:33], v[74:77], v[70:73], v[18:33]
	ds_read_b128 v[70:73], v107 offset:32
	ds_read_b128 v[102:105], v107 offset:64
	v_or_b32_e32 v108, s25, v159
	s_add_i32 s6, s6, 1
	s_add_u32 s10, s10, 0x4000
	s_addc_u32 s11, s11, 0
	s_cmp_eq_u32 s10, 0xa8000
	s_waitcnt lgkmcnt(1)
	v_mfma_f32_32x32x16_bf16 v[50:65], v[74:77], v[70:73], v[50:65]
	ds_read_b128 v[172:175], v106 offset:23104
	ds_read_b128 v[176:179], v107 offset:4672
	global_load_dwordx4 v[74:77], v244, s[76:77] offset:-4096
	s_nop 0
	global_load_dwordx4 v[78:81], v244, s[76:77]
	v_mfma_f32_32x32x16_bf16 v[34:49], v[66:69], v[70:73], v[34:49]
	global_load_dwordx4 v[66:69], v242, s[62:63]
	global_load_dwordx4 v[70:73], v243, s[62:63]
	ds_read_b128 v[180:183], v106 offset:18528
	ds_read_b128 v[184:187], v107 offset:96
	s_waitcnt lgkmcnt(4)
	v_mfma_f32_32x32x16_bf16 v[50:65], v[98:101], v[102:105], v[50:65]
	ds_read_b128 v[188:191], v106 offset:23136
	ds_read_b128 v[192:195], v107 offset:4704
	s_waitcnt lgkmcnt(0)
	s_barrier
	v_mfma_f32_32x32x16_bf16 v[34:49], v[172:175], v[102:105], v[34:49]
	v_add_u32_e32 v102, v108, v160
	v_add_u32_e32 v103, v108, v161
	ds_read_b128 v[106:109], v102 offset:18432
	ds_read_b128 v[110:113], v103
	v_mfma_f32_32x32x16_bf16 v[18:33], v[98:101], v[176:179], v[18:33]
	ds_read_b128 v[98:101], v102 offset:23040
	ds_read_b128 v[102:105], v103 offset:4608
	v_mfma_f32_32x32x16_bf16 v[2:17], v[172:175], v[176:179], v[2:17]
	v_mfma_f32_32x32x16_bf16 v[50:65], v[180:183], v[184:187], v[50:65]
	v_mfma_f32_32x32x16_bf16 v[34:49], v[188:191], v[184:187], v[34:49]
	v_mfma_f32_32x32x16_bf16 v[18:33], v[180:183], v[192:195], v[18:33]
	v_mfma_f32_32x32x16_bf16 v[2:17], v[188:191], v[192:195], v[2:17]
	s_cbranch_scc0 .LBB0_2477
	s_waitcnt lgkmcnt(2)
	v_mfma_f32_32x32x16_bf16 v[50:65], v[106:109], v[110:113], v[50:65]
	s_waitcnt vmcnt(7)
	ds_write_b128 v152, v[90:93] offset:36864
	s_waitcnt vmcnt(6)
	ds_write_b128 v152, v[94:97] offset:55296
	s_lshl_b32 s6, s23, 7
	s_mov_b64 s[10:11], -1
	s_waitcnt lgkmcnt(3)
	v_mfma_f32_32x32x16_bf16 v[34:49], v[98:101], v[110:113], v[34:49]
	s_waitcnt vmcnt(5)
	ds_write_b128 v154, v[82:85] offset:36864
	s_waitcnt vmcnt(4)
	ds_write_b128 v154, v[86:89] offset:55296
	s_waitcnt lgkmcnt(4)
	v_mfma_f32_32x32x16_bf16 v[18:33], v[106:109], v[102:105], v[18:33]
	s_waitcnt vmcnt(1)
	ds_write_b128 v156, v[66:69] offset:36864
	ds_write_b128 v156, v[74:77] offset:55296
	v_mfma_f32_32x32x16_bf16 v[2:17], v[98:101], v[102:105], v[2:17]
	s_waitcnt vmcnt(0)
	ds_write_b128 v158, v[70:73] offset:36864
	ds_write_b128 v158, v[78:81] offset:55296
	ds_read_b128 v[66:69], v162 offset:23072
	ds_read_b128 v[70:73], v163 offset:4640
	s_waitcnt lgkmcnt(0)
	v_mfma_f32_32x32x16_bf16 v[2:17], v[66:69], v[70:73], v[2:17]
	ds_read_b128 v[74:77], v162 offset:18464
	ds_read_b128 v[78:81], v162 offset:18496
	s_waitcnt lgkmcnt(1)
	v_mfma_f32_32x32x16_bf16 v[18:33], v[74:77], v[70:73], v[18:33]
	ds_read_b128 v[70:73], v163 offset:32
	ds_read_b128 v[82:85], v163 offset:64
	s_waitcnt lgkmcnt(1)
	v_mfma_f32_32x32x16_bf16 v[50:65], v[74:77], v[70:73], v[50:65]
	ds_read_b128 v[74:77], v162 offset:23104
	ds_read_b128 v[86:89], v163 offset:4672
	v_mfma_f32_32x32x16_bf16 v[34:49], v[66:69], v[70:73], v[34:49]
	ds_read_b128 v[66:69], v162 offset:18528
	ds_read_b128 v[70:73], v163 offset:96
	s_waitcnt lgkmcnt(4)
	v_mfma_f32_32x32x16_bf16 v[50:65], v[78:81], v[82:85], v[50:65]
	ds_read_b128 v[90:93], v162 offset:23136
	ds_read_b128 v[94:97], v163 offset:4704
	s_waitcnt lgkmcnt(0)
	s_barrier
	v_mfma_f32_32x32x16_bf16 v[34:49], v[74:77], v[82:85], v[34:49]
	ds_read_b128 v[82:85], v169 offset:55296
	ds_read_b128 v[98:101], v170 offset:36864
	v_mfma_f32_32x32x16_bf16 v[18:33], v[78:81], v[86:89], v[18:33]
	ds_read_b128 v[78:81], v169 offset:59904
	ds_read_b128 v[102:105], v170 offset:41472
	v_mfma_f32_32x32x16_bf16 v[2:17], v[74:77], v[86:89], v[2:17]
	ds_read_b128 v[74:77], v162 offset:59936
	ds_read_b128 v[86:89], v163 offset:41504
	v_mfma_f32_32x32x16_bf16 v[50:65], v[66:69], v[70:73], v[50:65]
	ds_read_b128 v[106:109], v162 offset:55328
	ds_read_b128 v[110:113], v162 offset:55360
	v_mfma_f32_32x32x16_bf16 v[34:49], v[90:93], v[70:73], v[34:49]
	ds_read_b128 v[70:73], v163 offset:36896
	ds_read_b128 v[140:143], v163 offset:36928
	v_mfma_f32_32x32x16_bf16 v[18:33], v[66:69], v[94:97], v[18:33]
	ds_read_b128 v[66:69], v162 offset:59968
	ds_read_b128 v[144:147], v163 offset:41536
	v_mfma_f32_32x32x16_bf16 v[2:17], v[90:93], v[94:97], v[2:17]
	ds_read_b128 v[90:93], v162 offset:55392
	ds_read_b128 v[94:97], v163 offset:36960
	s_waitcnt lgkmcnt(12)
	v_mfma_f32_32x32x16_bf16 v[50:65], v[82:85], v[98:101], v[50:65]
	ds_read_b128 v[172:175], v162 offset:60000
	ds_read_b128 v[176:179], v163 offset:41568
	s_waitcnt lgkmcnt(0)
	s_barrier
	s_barrier
	v_mfma_f32_32x32x16_bf16 v[34:49], v[78:81], v[98:101], v[34:49]
	v_mfma_f32_32x32x16_bf16 v[18:33], v[82:85], v[102:105], v[18:33]
	v_mfma_f32_32x32x16_bf16 v[2:17], v[78:81], v[102:105], v[2:17]
	v_mfma_f32_32x32x16_bf16 v[50:65], v[106:109], v[70:73], v[50:65]
	v_mfma_f32_32x32x16_bf16 v[34:49], v[74:77], v[70:73], v[34:49]
	v_mfma_f32_32x32x16_bf16 v[18:33], v[106:109], v[86:89], v[18:33]
	v_mfma_f32_32x32x16_bf16 v[2:17], v[74:77], v[86:89], v[2:17]
	v_mfma_f32_32x32x16_bf16 v[50:65], v[110:113], v[140:143], v[50:65]
	v_mfma_f32_32x32x16_bf16 v[34:49], v[66:69], v[140:143], v[34:49]
	v_mfma_f32_32x32x16_bf16 v[18:33], v[110:113], v[144:147], v[18:33]
	v_mfma_f32_32x32x16_bf16 v[2:17], v[66:69], v[144:147], v[2:17]
	v_mfma_f32_32x32x16_bf16 v[50:65], v[90:93], v[94:97], v[50:65]
	s_nop 11
	ds_write_b128 v164, v[50:53]
	ds_write_b128 v164, v[54:57] offset:32
	v_mfma_f32_32x32x16_bf16 v[34:49], v[172:175], v[94:97], v[34:49]
	ds_write_b128 v164, v[58:61] offset:64
	ds_write_b128 v164, v[62:65] offset:96
	v_mfma_f32_32x32x16_bf16 v[18:33], v[90:93], v[176:179], v[18:33]
	s_nop 8
	ds_write_b128 v164, v[34:37] offset:128
	ds_write_b128 v164, v[38:41] offset:160
	v_mfma_f32_32x32x16_bf16 v[2:17], v[172:175], v[176:179], v[2:17]
	ds_write_b128 v164, v[42:45] offset:192
	ds_write_b128 v164, v[46:49] offset:224
	ds_write_b128 v164, v[18:21] offset:16896
	ds_write_b128 v164, v[22:25] offset:16928
	ds_write_b128 v164, v[26:29] offset:16960
	ds_write_b128 v164, v[30:33] offset:16992
	s_nop 5
	ds_write_b128 v164, v[2:5] offset:17024
	v_lshl_or_b32 v4, s24, 7, v165
	s_load_dwordx4 s[24:27], s[0:1], 0xe0
	ds_write_b128 v164, v[6:9] offset:17056
	v_ashrrev_i32_e32 v7, 6, v4
	v_lshl_add_u32 v2, s23, 4, v7
	v_ashrrev_i32_e32 v3, 31, v2
	v_ashrrev_i32_e32 v5, 31, v4
	v_lshlrev_b64 v[2:3], 14, v[2:3]
	v_or_b32_e32 v6, s6, v1
	v_lshl_add_u64 v[2:3], s[92:93], 0, v[2:3]
	s_waitcnt lgkmcnt(0)
	v_lshl_add_u64 v[4:5], v[4:5], 2, s[26:27]
	s_or_b32 s23, s6, 32
	s_or_b32 s24, s6, 40
	s_or_b32 s25, s6, 48
	s_or_b32 s26, s6, 56
	s_mov_b32 s27, 0
	ds_write_b128 v164, v[10:13] offset:17088
	ds_write_b128 v164, v[14:17] offset:17120
	s_waitcnt lgkmcnt(0)
	s_barrier
